# attention tile loop: exp/sum/pack blocks interleaved between the MFMAs of the matrix block they are independent of (renamed registers, packed f32 adds unpacked)
# speedup vs baseline: 1.0491x; 1.0062x over previous
; #define SBAR() __builtin_amdgcn_sched_barrier(0)
; #define SBAR() __builtin_amdgcn_sched_barrier(0)
; __device__ __forceinline__ void softHalf(f32x16& p, float& l_reg, bf16x8& paLo, bf16x8& paHi) {
; #pragma unroll
;     for (int r = 0; r < 16; ++r) p[r] = __builtin_amdgcn_exp2f(p[r]);
;     float ps = 0;
; #pragma unroll
;     for (int r = 0; r < 16; ++r) ps += p[r];
;     l_reg += ps;
;     ...
;     PK4(p, 0, paLo); PK4(p, 8, paHi);
;     ...
; }
; __device__ __forceinline__ void qkt(f32x16& p0, f32x16& p1, const char* Ks, const bf16x8* qr, int r32, int hi) {
;     p0 = f32x16{}; p1 = f32x16{};
; #pragma unroll
;     for (int d0 = 0; d0 < 4; ++d0) { const int cb = (d0 * 16 + hi * 8) * 2;
;         const bf16x8 b0 = *reinterpret_cast<const bf16x8*>(Ks + KSWZ64(r32, cb));
;         const bf16x8 b1 = *reinterpret_cast<const bf16x8*>(Ks + KSWZ64(32 + r32, cb));
;         p0 = __builtin_amdgcn_mfma_f32_32x32x16_bf16(b0, qr[d0], p0, 0, 0, 0);
;         p1 = __builtin_amdgcn_mfma_f32_32x32x16_bf16(b1, qr[d0], p1, 0, 0, 0); }
; }
; __device__ __forceinline__ int v_st(int k, int c) { const int kk = (k & ~0xC) | ((k & 4) << 1) | ((k & 8) >> 1); return ((kk >> 3) * 4 + (c >> 5)) * 512 + ((kk & 7) * 32 + (c & 31)) * 2; }
; __device__ __forceinline__ int v_rd_base(int lane) { return ((lane & 3) << 3) | (((lane >> 2) & 3) << 6) | (((lane >> 4) & 1) << 5) | (((lane >> 5) & 1) << 8); }
; template <int OFF> __device__ __forceinline__ s16x4 tr_read(int vb) {
;     s16x4 r; asm volatile("ds_read_b64_tr_b16 %0, %1 offset:%2" : "=&v"(r) : "v"(vb), "i"(OFF) : "memory"); return r;
; }
; template <int D0> __device__ __forceinline__ void pv_one(f32x16& od, int vb, bf16x8 pa0, bf16x8 pa1, bf16x8 pa2, bf16x8 pa3) {
;     const s16x4 l0 = tr_read<v_rd_off(D0, 0, 0)>(vb), h0 = tr_read<v_rd_off(D0, 0, 1)>(vb), l1 = tr_read<v_rd_off(D0, 1, 0)>(vb), h1 = tr_read<v_rd_off(D0, 1, 1)>(vb);
; __device__ __forceinline__ void attn_unit(const bf16* __restrict__ Qb, const bf16* __restrict__ Kh, const bf16* __restrict__ Vh, bf16* __restrict__ Ob, int seq, char* lds) {
;     ...
;         SBAR(); qkt(pB0, pB1, K_lds + SHM_K, qr, r32, hi); pv_ks<0>(o, vb0, pa0); SBAR();
;         softHalf(pA1, l_reg, pa2, pa3); SBAR();
;         SLOAD(SO, (j + 1) * KVBLK); SBAR();
;         pv_ks<1>(o, vb0, pa1); pv_ks<2>(o, vb0, pa2); pv_ks<3>(o, vb0, pa3); SBAR();
;         softHalf(pB0, l_reg, pa0, pa1); SBAR();
.LBB0_531:
	ds_read_b128 v[82:85], v157 offset:40960
	ds_read_b128 v[86:89], v157 offset:45056
	ds_read_b128 v[164:167], v159 offset:40960
	ds_read_b128 v[168:171], v159 offset:45056
	v_exp_f32_e32 v66, v66
	v_exp_f32_e32 v67, v67
	v_exp_f32_e32 v68, v68
	v_exp_f32_e32 v69, v69
	s_waitcnt lgkmcnt(3)
	v_mfma_f32_32x32x16_bf16 v[98:113], v[82:85], v[126:129], 0
	v_exp_f32_e32 v70, v70
	v_add_f32_e32 v179, 0, v66
	v_exp_f32_e32 v71, v71
	s_waitcnt lgkmcnt(2)
	v_mfma_f32_32x32x16_bf16 v[82:97], v[86:89], v[126:129], 0
	v_add_f32_e32 v179, v67, v179
	v_exp_f32_e32 v72, v72
	v_add_f32_e32 v179, v68, v179
	v_exp_f32_e32 v73, v73
	s_waitcnt lgkmcnt(1)
	v_mfma_f32_32x32x16_bf16 v[98:113], v[164:167], v[122:125], v[98:113]
	v_add_f32_e32 v179, v69, v179
	v_exp_f32_e32 v74, v74
	v_add_f32_e32 v179, v70, v179
	v_exp_f32_e32 v75, v75
	s_waitcnt lgkmcnt(0)
	v_mfma_f32_32x32x16_bf16 v[82:97], v[168:171], v[122:125], v[82:97]
	ds_read_b128 v[164:167], v162 offset:40960
	ds_read_b128 v[168:171], v162 offset:45056
	v_add_f32_e32 v179, v71, v179
	v_exp_f32_e32 v76, v76
	v_add_f32_e32 v179, v72, v179
	s_waitcnt lgkmcnt(1)
	v_mfma_f32_32x32x16_bf16 v[98:113], v[164:167], v[118:121], v[98:113]
	v_exp_f32_e32 v77, v77
	v_add_f32_e32 v179, v73, v179
	v_exp_f32_e32 v78, v78
	v_add_f32_e32 v179, v74, v179
	s_waitcnt lgkmcnt(0)
	v_mfma_f32_32x32x16_bf16 v[82:97], v[168:171], v[118:121], v[82:97]
	ds_read_b128 v[164:167], v163 offset:40960
	ds_read_b128 v[168:171], v163 offset:45056
	ds_read_b64_tr_b16 v[172:173], v156 offset:0
	ds_read_b64_tr_b16 v[174:175], v156 offset:0x800
	v_exp_f32_e32 v79, v79
	v_add_f32_e32 v179, v75, v179
	v_exp_f32_e32 v80, v80
	s_waitcnt lgkmcnt(1)
	v_mfma_f32_32x32x16_bf16 v[98:113], v[164:167], v[114:117], v[98:113]
	ds_read_b64_tr_b16 v[164:165], v156 offset:0x200
	ds_read_b64_tr_b16 v[166:167], v156 offset:0xa00
	ds_read_b64_tr_b16 v[180:181], v156 offset:0x400
	ds_read_b64_tr_b16 v[182:183], v156 offset:0xc00
	ds_read_b64_tr_b16 v[184:185], v156 offset:0x600
	ds_read_b64_tr_b16 v[186:187], v156 offset:0xe00
	v_add_f32_e32 v179, v76, v179
	v_exp_f32_e32 v81, v81
	v_add_f32_e32 v179, v77, v179
	v_add_f32_e32 v179, v78, v179
	v_add_f32_e32 v179, v79, v179
	s_waitcnt lgkmcnt(0)
	s_waitcnt lgkmcnt(0)
	v_mfma_f32_32x32x16_bf16 v[82:97], v[168:171], v[114:117], v[82:97]
	v_add_f32_e32 v179, v80, v179
	v_add_f32_e32 v179, v81, v179
	v_cvt_pk_bf16_f32 v66, v66, v67
	v_cvt_pk_bf16_f32 v67, v68, v69
	v_mfma_f32_32x32x16_bf16 v[2:17], v[134:137], v[172:175], v[2:17]
	v_cvt_pk_bf16_f32 v68, v70, v71
	v_cvt_pk_bf16_f32 v69, v72, v73
	v_cvt_pk_bf16_f32 v70, v74, v75
	v_cvt_pk_bf16_f32 v71, v76, v77
	v_cvt_pk_bf16_f32 v72, v78, v79
	v_mfma_f32_32x32x16_bf16 v[18:33], v[134:137], v[164:167], v[18:33]
	v_cvt_pk_bf16_f32 v73, v80, v81
	v_add_f32_e32 v221, v139, v179
	v_permlane32_swap_b32_e32 v66, v68
	v_mfma_f32_32x32x16_bf16 v[34:49], v[134:137], v[180:183], v[34:49]
	v_permlane32_swap_b32_e32 v67, v69
	v_permlane32_swap_b32_e32 v70, v72
	v_permlane32_swap_b32_e32 v71, v73
	v_mfma_f32_32x32x16_bf16 v[50:65], v[134:137], v[184:187], v[50:65]
	v_lshl_add_u64 v[136:137], s[30:31], 0, v[148:149]
	v_add_co_u32_e32 v74, vcc, s40, v136
	v_lshl_add_u64 v[150:151], s[30:31], 0, v[146:147]
	s_nop 0
	v_addc_co_u32_e32 v75, vcc, 0, v137, vcc
	v_add_co_u32_e32 v78, vcc, s41, v136
	s_nop 1
	v_addc_co_u32_e32 v79, vcc, 0, v137, vcc
	v_add_co_u32_e32 v164, vcc, s42, v150
	global_load_dwordx4 v[74:77], v[74:75], off
	s_nop 0
	global_load_dwordx4 v[78:81], v[78:79], off
	v_addc_co_u32_e32 v165, vcc, 0, v151, vcc
	global_load_dwordx4 v[164:167], v[164:165], off
	ds_read_b64_tr_b16 v[168:169], v156 offset:0x1000
	ds_read_b64_tr_b16 v[170:171], v156 offset:0x1800
	ds_read_b64_tr_b16 v[172:173], v156 offset:0x1200
	ds_read_b64_tr_b16 v[174:175], v156 offset:0x1a00
	ds_read_b64_tr_b16 v[180:181], v156 offset:0x1400
	ds_read_b64_tr_b16 v[182:183], v156 offset:0x1c00
	ds_read_b64_tr_b16 v[184:185], v156 offset:0x1600
	ds_read_b64_tr_b16 v[186:187], v156 offset:0x1e00
	v_exp_f32_e32 v220, v98
	v_exp_f32_e32 v177, v99
	v_exp_f32_e32 v193, v100
	v_exp_f32_e32 v195, v101
	s_waitcnt lgkmcnt(0)
	s_nop 0
	v_mfma_f32_32x32x16_bf16 v[2:17], v[130:133], v[168:171], v[2:17]
	ds_read_b64_tr_b16 v[168:169], v156 offset:0x2000
	ds_read_b64_tr_b16 v[170:171], v156 offset:0x2800
	v_exp_f32_e32 v197, v102
	v_exp_f32_e32 v199, v103
	v_exp_f32_e32 v201, v104
	v_mfma_f32_32x32x16_bf16 v[18:33], v[130:133], v[172:175], v[18:33]
	ds_read_b64_tr_b16 v[172:173], v156 offset:0x2200
	ds_read_b64_tr_b16 v[174:175], v156 offset:0x2a00
	v_exp_f32_e32 v203, v105
	v_cvt_pk_bf16_f32 v222, v220, v177
	v_cvt_pk_bf16_f32 v223, v193, v195
	v_mfma_f32_32x32x16_bf16 v[34:49], v[130:133], v[180:183], v[34:49]
	ds_read_b64_tr_b16 v[180:181], v156 offset:0x2400
	ds_read_b64_tr_b16 v[182:183], v156 offset:0x2c00
	ds_read_b64_tr_b16 v[188:189], v156 offset:0x2600
	ds_read_b64_tr_b16 v[190:191], v156 offset:0x2e00
	v_cvt_pk_bf16_f32 v224, v197, v199
	v_cvt_pk_bf16_f32 v225, v201, v203
	v_exp_f32_e32 v205, v106
	v_exp_f32_e32 v207, v107
	s_waitcnt lgkmcnt(0)
; #define SBAR() __builtin_amdgcn_sched_barrier(0)
; __device__ __forceinline__ void softHalf(f32x16& p, float& l_reg, bf16x8& paLo, bf16x8& paHi) {
; #pragma unroll
;     for (int r = 0; r < 16; ++r) p[r] = __builtin_amdgcn_exp2f(p[r]);
;     float ps = 0;
; #pragma unroll
;     for (int r = 0; r < 16; ++r) ps += p[r];
;     l_reg += ps;
;     ...
;     PK4(p, 0, paLo); PK4(p, 8, paHi);
;     ...
; }
; __device__ __forceinline__ void qkt(f32x16& p0, f32x16& p1, const char* Ks, const bf16x8* qr, int r32, int hi) {
;     p0 = f32x16{}; p1 = f32x16{};
; #pragma unroll
;     for (int d0 = 0; d0 < 4; ++d0) { const int cb = (d0 * 16 + hi * 8) * 2;
;         const bf16x8 b0 = *reinterpret_cast<const bf16x8*>(Ks + KSWZ64(r32, cb));
;         const bf16x8 b1 = *reinterpret_cast<const bf16x8*>(Ks + KSWZ64(32 + r32, cb));
;         p0 = __builtin_amdgcn_mfma_f32_32x32x16_bf16(b0, qr[d0], p0, 0, 0, 0);
;         p1 = __builtin_amdgcn_mfma_f32_32x32x16_bf16(b1, qr[d0], p1, 0, 0, 0); }
; }
; __device__ __forceinline__ int v_st(int k, int c) { const int kk = (k & ~0xC) | ((k & 4) << 1) | ((k & 8) >> 1); return ((kk >> 3) * 4 + (c >> 5)) * 512 + ((kk & 7) * 32 + (c & 31)) * 2; }
; __device__ __forceinline__ int v_rd_base(int lane) { return ((lane & 3) << 3) | (((lane >> 2) & 3) << 6) | (((lane >> 4) & 1) << 5) | (((lane >> 5) & 1) << 8); }
; template <int OFF> __device__ __forceinline__ s16x4 tr_read(int vb) {
;     s16x4 r; asm volatile("ds_read_b64_tr_b16 %0, %1 offset:%2" : "=&v"(r) : "v"(vb), "i"(OFF) : "memory"); return r;
; }
; template <int D0> __device__ __forceinline__ void pv_one(f32x16& od, int vb, bf16x8 pa0, bf16x8 pa1, bf16x8 pa2, bf16x8 pa3) {
; __device__ __forceinline__ void attn_unit(const bf16* __restrict__ Qb, const bf16* __restrict__ Kh, const bf16* __restrict__ Vh, bf16* __restrict__ Ob, int seq, char* lds) {
;     ...
;         pv_ks<1>(o, vb0, pa1); pv_ks<2>(o, vb0, pa2); pv_ks<3>(o, vb0, pa3); SBAR();
;         softHalf(pB0, l_reg, pa0, pa1); SBAR();
;         __syncthreads(); SWAIT(); SWRITE(0, SE);
;         __syncthreads();
;         SBAR(); qkt(pA0, pA1, K_lds, qr, r32, hi); pv_ks<0>(o, vb0 + SHM_V, pa0); SBAR();
;         softHalf(pB1, l_reg, pa2, pa3); SBAR();
;         SLOAD(SE, (j + 2) * KVBLK); SBAR();
;         pv_ks<1>(o, vb0 + SHM_V, pa1); pv_ks<2>(o, vb0 + SHM_V, pa2); pv_ks<3>(o, vb0 + SHM_V, pa3); SBAR();
;         softHalf(pA0, l_reg, pa0, pa1); SBAR();
	v_mfma_f32_32x32x16_bf16 v[50:65], v[130:133], v[184:187], v[50:65]
	ds_read_b64_tr_b16 v[130:131], v156 offset:0x3000
	ds_read_b64_tr_b16 v[132:133], v156 offset:0x3800
	v_exp_f32_e32 v209, v108
	v_exp_f32_e32 v211, v109
	v_mfma_f32_32x32x16_bf16 v[2:17], v[66:69], v[168:171], v[2:17]
	ds_read_b64_tr_b16 v[168:169], v156 offset:0x3200
	ds_read_b64_tr_b16 v[170:171], v156 offset:0x3a00
	v_exp_f32_e32 v213, v110
	v_exp_f32_e32 v215, v111
	v_exp_f32_e32 v217, v112
	v_mfma_f32_32x32x16_bf16 v[18:33], v[66:69], v[172:175], v[18:33]
	ds_read_b64_tr_b16 v[172:173], v156 offset:0x3400
	ds_read_b64_tr_b16 v[174:175], v156 offset:0x3c00
	v_exp_f32_e32 v219, v113
	v_add_f32_e32 v139, 0, v220
	v_add_f32_e32 v238, v177, v139
	v_add_f32_e32 v238, v193, v238
	v_add_f32_e32 v238, v195, v238
	v_mfma_f32_32x32x16_bf16 v[34:49], v[66:69], v[180:183], v[34:49]
	ds_read_b64_tr_b16 v[180:181], v156 offset:0x3600
	ds_read_b64_tr_b16 v[182:183], v156 offset:0x3e00
	v_add_f32_e32 v238, v197, v238
	v_add_f32_e32 v238, v199, v238
	v_add_f32_e32 v238, v201, v238
	v_add_f32_e32 v238, v203, v238
	v_add_f32_e32 v238, v205, v238
	s_waitcnt lgkmcnt(0)
	v_mfma_f32_32x32x16_bf16 v[50:65], v[66:69], v[188:191], v[50:65]
	v_add_f32_e32 v238, v207, v238
	v_add_f32_e32 v238, v209, v238
	v_add_f32_e32 v238, v211, v238
	v_add_f32_e32 v238, v213, v238
	v_add_f32_e32 v238, v215, v238
	v_add_f32_e32 v238, v217, v238
	v_mfma_f32_32x32x16_bf16 v[2:17], v[70:73], v[130:133], v[2:17]
	v_add_f32_e32 v238, v219, v238
	v_add_f32_e32 v238, v221, v238
	v_permlane32_swap_b32_e32 v222, v224
	v_permlane32_swap_b32_e32 v223, v225
	v_mfma_f32_32x32x16_bf16 v[18:33], v[70:73], v[168:171], v[18:33]
	v_cvt_pk_bf16_f32 v226, v205, v207
	v_cvt_pk_bf16_f32 v227, v209, v211
	v_cvt_pk_bf16_f32 v228, v213, v215
	v_cvt_pk_bf16_f32 v229, v217, v219
	v_mfma_f32_32x32x16_bf16 v[34:49], v[70:73], v[172:175], v[34:49]
	s_nop 0
	v_permlane32_swap_b32_e32 v226, v228
	v_permlane32_swap_b32_e32 v227, v229
	v_mfma_f32_32x32x16_bf16 v[50:65], v[70:73], v[180:183], v[50:65]
	s_barrier
	s_waitcnt vmcnt(0)
	s_waitcnt vmcnt(2)
	ds_write_b128 v160, v[74:77]
	s_waitcnt vmcnt(1)
	ds_write_b128 v161, v[78:81]
	s_waitcnt vmcnt(0)
	ds_write_b128 v158, v[164:167] offset:32768
	s_waitcnt lgkmcnt(0)
	s_barrier
	ds_read_b128 v[66:69], v157 offset:32768
	ds_read_b128 v[70:73], v157 offset:36864
	ds_read_b128 v[164:167], v159 offset:32768
	ds_read_b128 v[172:175], v159 offset:36864
	v_exp_f32_e32 v176, v82
	v_exp_f32_e32 v192, v83
	v_exp_f32_e32 v194, v84
	v_exp_f32_e32 v196, v85
	s_waitcnt lgkmcnt(3)
	v_mfma_f32_32x32x16_bf16 v[98:113], v[66:69], v[126:129], 0
	v_exp_f32_e32 v198, v86
	v_add_f32_e32 v82, v176, v138
	v_exp_f32_e32 v200, v87
	v_add_f32_e32 v82, v192, v82
	s_waitcnt lgkmcnt(2)
	v_mfma_f32_32x32x16_bf16 v[66:81], v[70:73], v[126:129], 0
	v_exp_f32_e32 v202, v88
	v_add_f32_e32 v82, v194, v82
	v_exp_f32_e32 v204, v89
	s_waitcnt lgkmcnt(1)
	v_mfma_f32_32x32x16_bf16 v[98:113], v[164:167], v[122:125], v[98:113]
	v_add_f32_e32 v82, v196, v82
	v_exp_f32_e32 v206, v90
	v_add_f32_e32 v82, v198, v82
	v_exp_f32_e32 v208, v91
	s_waitcnt lgkmcnt(0)
	v_mfma_f32_32x32x16_bf16 v[66:81], v[172:175], v[122:125], v[66:81]
	ds_read_b128 v[164:167], v162 offset:32768
	ds_read_b128 v[172:175], v162 offset:36864
	v_add_f32_e32 v82, v200, v82
	v_exp_f32_e32 v210, v92
	v_add_f32_e32 v82, v202, v82
	s_waitcnt lgkmcnt(1)
	v_mfma_f32_32x32x16_bf16 v[98:113], v[164:167], v[118:121], v[98:113]
	v_exp_f32_e32 v212, v93
	v_add_f32_e32 v82, v204, v82
	v_exp_f32_e32 v214, v94
	v_add_f32_e32 v82, v206, v82
	s_waitcnt lgkmcnt(0)
	v_mfma_f32_32x32x16_bf16 v[66:81], v[172:175], v[118:121], v[66:81]
	ds_read_b128 v[164:167], v163 offset:32768
	ds_read_b128 v[172:175], v163 offset:36864
	ds_read_b64_tr_b16 v[180:181], v141 offset:0
	ds_read_b64_tr_b16 v[182:183], v141 offset:0x800
	v_exp_f32_e32 v216, v95
	v_add_f32_e32 v82, v208, v82
	v_exp_f32_e32 v218, v96
	v_add_f32_e32 v82, v210, v82
	s_waitcnt lgkmcnt(1)
	v_mfma_f32_32x32x16_bf16 v[98:113], v[164:167], v[114:117], v[98:113]
	ds_read_b64_tr_b16 v[164:165], v141 offset:0x200
	ds_read_b64_tr_b16 v[166:167], v141 offset:0xa00
	ds_read_b64_tr_b16 v[184:185], v141 offset:0x400
	ds_read_b64_tr_b16 v[186:187], v141 offset:0xc00
	ds_read_b64_tr_b16 v[188:189], v141 offset:0x600
	ds_read_b64_tr_b16 v[190:191], v141 offset:0xe00
	v_exp_f32_e32 v220, v97
	v_add_f32_e32 v82, v212, v82
	v_add_f32_e32 v82, v214, v82
	v_add_f32_e32 v82, v216, v82
	s_waitcnt lgkmcnt(0)
	s_waitcnt lgkmcnt(0)
	v_mfma_f32_32x32x16_bf16 v[66:81], v[172:175], v[114:117], v[66:81]
	v_add_f32_e32 v82, v218, v82
	v_add_f32_e32 v82, v220, v82
	v_add_f32_e32 v139, v82, v238
	v_cvt_pk_bf16_f32 v82, v176, v192
	v_cvt_pk_bf16_f32 v83, v194, v196
	v_mfma_f32_32x32x16_bf16 v[2:17], v[222:225], v[180:183], v[2:17]
	v_cvt_pk_bf16_f32 v84, v198, v200
	v_cvt_pk_bf16_f32 v85, v202, v204
	v_cvt_pk_bf16_f32 v86, v206, v208
	v_cvt_pk_bf16_f32 v87, v210, v212
	v_mfma_f32_32x32x16_bf16 v[18:33], v[222:225], v[164:167], v[18:33]
	v_cvt_pk_bf16_f32 v88, v214, v216
	v_cvt_pk_bf16_f32 v89, v218, v220
	s_nop 0
	v_permlane32_swap_b32_e32 v82, v84
	v_mfma_f32_32x32x16_bf16 v[34:49], v[222:225], v[184:187], v[34:49]
	v_permlane32_swap_b32_e32 v83, v85
	v_permlane32_swap_b32_e32 v86, v88
	v_permlane32_swap_b32_e32 v87, v89
	v_mfma_f32_32x32x16_bf16 v[50:65], v[222:225], v[188:191], v[50:65]
	v_add_co_u32_e32 v90, vcc, s43, v136
	s_nop 1
	v_addc_co_u32_e32 v91, vcc, 0, v137, vcc
	v_add_co_u32_e32 v94, vcc, s46, v136
	s_nop 1
	v_addc_co_u32_e32 v95, vcc, 0, v137, vcc
	v_add_co_u32_e32 v130, vcc, s47, v150
	global_load_dwordx4 v[90:93], v[90:91], off
	s_nop 0
	global_load_dwordx4 v[94:97], v[94:95], off
	v_addc_co_u32_e32 v131, vcc, 0, v151, vcc
	global_load_dwordx4 v[164:167], v[130:131], off
	ds_read_b64_tr_b16 v[230:231], v141 offset:0x1000
	ds_read_b64_tr_b16 v[232:233], v141 offset:0x1800
	ds_read_b64_tr_b16 v[234:235], v141 offset:0x1200
	ds_read_b64_tr_b16 v[236:237], v141 offset:0x1a00
	ds_read_b64_tr_b16 v[172:173], v141 offset:0x1400
	ds_read_b64_tr_b16 v[174:175], v141 offset:0x1c00
	ds_read_b64_tr_b16 v[180:181], v141 offset:0x1600
	ds_read_b64_tr_b16 v[182:183], v141 offset:0x1e00
	v_exp_f32_e32 v239, v98
	v_exp_f32_e32 v241, v99
	v_exp_f32_e32 v242, v100
	v_exp_f32_e32 v243, v101
	s_waitcnt lgkmcnt(0)
; #define SBAR() __builtin_amdgcn_sched_barrier(0)
; #define SWAIT() asm volatile("s_waitcnt vmcnt(0)" ::: "memory")
; #define SBAR() __builtin_amdgcn_sched_barrier(0)
; __device__ __forceinline__ void softHalf(f32x16& p, float& l_reg, bf16x8& paLo, bf16x8& paHi) {
; #pragma unroll
;     for (int r = 0; r < 16; ++r) p[r] = __builtin_amdgcn_exp2f(p[r]);
;     float ps = 0;
; #pragma unroll
;     for (int r = 0; r < 16; ++r) ps += p[r];
;     l_reg += ps;
;     ...
;     PK4(p, 0, paLo); PK4(p, 8, paHi);
;     ...
; }
; __device__ __forceinline__ void qkt(f32x16& p0, f32x16& p1, const char* Ks, const bf16x8* qr, int r32, int hi) {
;     p0 = f32x16{}; p1 = f32x16{};
; #pragma unroll
;     for (int d0 = 0; d0 < 4; ++d0) { const int cb = (d0 * 16 + hi * 8) * 2;
;         const bf16x8 b0 = *reinterpret_cast<const bf16x8*>(Ks + KSWZ64(r32, cb));
;         const bf16x8 b1 = *reinterpret_cast<const bf16x8*>(Ks + KSWZ64(32 + r32, cb));
;         p0 = __builtin_amdgcn_mfma_f32_32x32x16_bf16(b0, qr[d0], p0, 0, 0, 0);
;         p1 = __builtin_amdgcn_mfma_f32_32x32x16_bf16(b1, qr[d0], p1, 0, 0, 0); }
; }
; __device__ __forceinline__ int v_st(int k, int c) { const int kk = (k & ~0xC) | ((k & 4) << 1) | ((k & 8) >> 1); return ((kk >> 3) * 4 + (c >> 5)) * 512 + ((kk & 7) * 32 + (c & 31)) * 2; }
; __device__ __forceinline__ int v_rd_base(int lane) { return ((lane & 3) << 3) | (((lane >> 2) & 3) << 6) | (((lane >> 4) & 1) << 5) | (((lane >> 5) & 1) << 8); }
; template <int OFF> __device__ __forceinline__ s16x4 tr_read(int vb) {
;     s16x4 r; asm volatile("ds_read_b64_tr_b16 %0, %1 offset:%2" : "=&v"(r) : "v"(vb), "i"(OFF) : "memory"); return r;
; }
; template <int D0> __device__ __forceinline__ void pv_one(f32x16& od, int vb, bf16x8 pa0, bf16x8 pa1, bf16x8 pa2, bf16x8 pa3) {
;     const s16x4 l0 = tr_read<v_rd_off(D0, 0, 0)>(vb), h0 = tr_read<v_rd_off(D0, 0, 1)>(vb), l1 = tr_read<v_rd_off(D0, 1, 0)>(vb), h1 = tr_read<v_rd_off(D0, 1, 1)>(vb);
; __device__ __forceinline__ void attn_unit(const bf16* __restrict__ Qb, const bf16* __restrict__ Kh, const bf16* __restrict__ Vh, bf16* __restrict__ Ob, int seq, char* lds) {
;     ...
;         SLOAD(SE, (j + 2) * KVBLK); SBAR();
;         pv_ks<1>(o, vb0 + SHM_V, pa1); pv_ks<2>(o, vb0 + SHM_V, pa2); pv_ks<3>(o, vb0 + SHM_V, pa3); SBAR();
;         softHalf(pA0, l_reg, pa0, pa1); SBAR();
;         __syncthreads(); SWAIT(); SWRITE(1, SO);
;         __syncthreads();
	s_nop 0
	v_mfma_f32_32x32x16_bf16 v[2:17], v[226:229], v[230:233], v[2:17]
	ds_read_b64_tr_b16 v[230:231], v141 offset:0x2000
	ds_read_b64_tr_b16 v[232:233], v141 offset:0x2800
	v_exp_f32_e32 v244, v102
	v_exp_f32_e32 v98, v106
	v_add_f32_e32 v106, 0, v239
	v_mfma_f32_32x32x16_bf16 v[18:33], v[226:229], v[234:237], v[18:33]
	ds_read_b64_tr_b16 v[234:235], v141 offset:0x2200
	ds_read_b64_tr_b16 v[236:237], v141 offset:0x2a00
	v_exp_f32_e32 v245, v103
	v_add_f32_e32 v106, v241, v106
	v_exp_f32_e32 v246, v104
	v_add_f32_e32 v106, v242, v106
	v_mfma_f32_32x32x16_bf16 v[34:49], v[226:229], v[172:175], v[34:49]
	ds_read_b64_tr_b16 v[172:173], v141 offset:0x2400
	ds_read_b64_tr_b16 v[174:175], v141 offset:0x2c00
	ds_read_b64_tr_b16 v[184:185], v141 offset:0x2600
	ds_read_b64_tr_b16 v[186:187], v141 offset:0x2e00
	v_exp_f32_e32 v247, v105
	v_add_f32_e32 v106, v243, v106
	v_add_f32_e32 v106, v244, v106
	v_exp_f32_e32 v99, v107
	s_waitcnt lgkmcnt(0)
	v_mfma_f32_32x32x16_bf16 v[50:65], v[226:229], v[180:183], v[50:65]
	v_add_f32_e32 v106, v245, v106
	v_exp_f32_e32 v100, v108
	v_add_f32_e32 v106, v246, v106
	v_mfma_f32_32x32x16_bf16 v[2:17], v[82:85], v[230:233], v[2:17]
	ds_read_b64_tr_b16 v[230:231], v141 offset:0x3000
	ds_read_b64_tr_b16 v[232:233], v141 offset:0x3800
	v_exp_f32_e32 v101, v109
	v_add_f32_e32 v106, v247, v106
	v_exp_f32_e32 v102, v110
	v_add_f32_e32 v106, v98, v106
	v_mfma_f32_32x32x16_bf16 v[18:33], v[82:85], v[234:237], v[18:33]
	ds_read_b64_tr_b16 v[234:235], v141 offset:0x3200
	ds_read_b64_tr_b16 v[236:237], v141 offset:0x3a00
	ds_read_b64_tr_b16 v[168:169], v141 offset:0x3400
	ds_read_b64_tr_b16 v[170:171], v141 offset:0x3c00
	v_exp_f32_e32 v103, v111
	v_add_f32_e32 v106, v99, v106
	v_exp_f32_e32 v104, v112
	v_mfma_f32_32x32x16_bf16 v[34:49], v[82:85], v[172:175], v[34:49]
	ds_read_b64_tr_b16 v[172:173], v141 offset:0x3600
	ds_read_b64_tr_b16 v[174:175], v141 offset:0x3e00
	v_add_f32_e32 v106, v100, v106
	v_exp_f32_e32 v105, v113
	v_add_f32_e32 v106, v101, v106
	v_add_f32_e32 v106, v102, v106
	v_add_f32_e32 v106, v103, v106
	s_waitcnt lgkmcnt(0)
	v_mfma_f32_32x32x16_bf16 v[50:65], v[82:85], v[184:187], v[50:65]
	v_add_f32_e32 v106, v104, v106
	v_add_f32_e32 v106, v105, v106
	v_cvt_pk_bf16_f32 v134, v239, v241
	v_cvt_pk_bf16_f32 v135, v242, v243
	v_mfma_f32_32x32x16_bf16 v[2:17], v[86:89], v[230:233], v[2:17]
	v_cvt_pk_bf16_f32 v136, v244, v245
	v_cvt_pk_bf16_f32 v137, v246, v247
	v_cvt_pk_bf16_f32 v130, v98, v99
	v_cvt_pk_bf16_f32 v131, v100, v101
	v_cvt_pk_bf16_f32 v132, v102, v103
	v_mfma_f32_32x32x16_bf16 v[18:33], v[86:89], v[234:237], v[18:33]
	v_cvt_pk_bf16_f32 v133, v104, v105
	v_add_f32_e32 v139, v139, v106
	v_permlane32_swap_b32_e32 v134, v136
	v_mfma_f32_32x32x16_bf16 v[34:49], v[86:89], v[168:171], v[34:49]
	v_permlane32_swap_b32_e32 v135, v137
	v_permlane32_swap_b32_e32 v130, v132
	v_permlane32_swap_b32_e32 v131, v133
	v_mfma_f32_32x32x16_bf16 v[50:65], v[86:89], v[172:175], v[50:65]
	s_barrier
	s_waitcnt vmcnt(0)
	s_add_i32 s10, s10, 2
	v_lshl_add_u64 v[146:147], v[146:147], 0, s[0:1]
	s_cmp_gt_u32 s10, 32
	v_lshl_add_u64 v[148:149], v[148:149], 0, s[4:5]
	s_waitcnt vmcnt(2)
	ds_write_b128 v160, v[90:93] offset:16384
	s_waitcnt vmcnt(1)
	ds_write_b128 v161, v[94:97] offset:16384
	s_waitcnt vmcnt(0)
	ds_write_b128 v158, v[164:167] offset:40960
	s_waitcnt lgkmcnt(0)
	s_barrier
	s_cbranch_scc0 .LBB0_531
	v_and_b32_e32 v82, 0x3fffffc0, v143
	v_lshl_add_u32 v143, v82, 2, 0
	ds_read_b128 v[82:85], v157 offset:40960
	ds_read_b128 v[86:89], v157 offset:45056
	s_waitcnt lgkmcnt(1)
	v_mfma_f32_32x32x16_bf16 v[98:113], v[82:85], v[126:129], 0
	s_waitcnt lgkmcnt(0)
	v_mfma_f32_32x32x16_bf16 v[82:97], v[86:89], v[126:129], 0
	ds_read_b128 v[126:129], v159 offset:40960
	ds_read_b128 v[146:149], v159 offset:45056
	s_waitcnt lgkmcnt(1)
	v_mfma_f32_32x32x16_bf16 v[98:113], v[126:129], v[122:125], v[98:113]
	s_waitcnt lgkmcnt(0)
	v_mfma_f32_32x32x16_bf16 v[82:97], v[146:149], v[122:125], v[82:97]
	ds_read_b128 v[122:125], v162 offset:40960
	ds_read_b128 v[126:129], v162 offset:45056
	s_waitcnt lgkmcnt(1)
	v_mfma_f32_32x32x16_bf16 v[98:113], v[122:125], v[118:121], v[98:113]
	s_waitcnt lgkmcnt(0)
	v_mfma_f32_32x32x16_bf16 v[82:97], v[126:129], v[118:121], v[82:97]
	ds_read_b128 v[118:121], v163 offset:40960
	ds_read_b128 v[122:125], v163 offset:45056
	ds_read_b64_tr_b16 v[126:127], v156 offset:0
	ds_read_b64_tr_b16 v[128:129], v156 offset:0x800
	s_waitcnt lgkmcnt(1)
	v_mfma_f32_32x32x16_bf16 v[98:113], v[118:121], v[114:117], v[98:113]
	ds_read_b64_tr_b16 v[118:119], v156 offset:0x200
	ds_read_b64_tr_b16 v[120:121], v156 offset:0xa00
	ds_read_b64_tr_b16 v[146:147], v156 offset:0x400
	ds_read_b64_tr_b16 v[148:149], v156 offset:0xc00
	ds_read_b64_tr_b16 v[158:159], v156 offset:0x600
	ds_read_b64_tr_b16 v[160:161], v156 offset:0xe00
	s_waitcnt lgkmcnt(0)
	s_waitcnt lgkmcnt(0)
; __device__ __forceinline__ void softHalf(f32x16& p, float& l_reg, bf16x8& paLo, bf16x8& paHi) {
; #pragma unroll
;     for (int r = 0; r < 16; ++r) p[r] = __builtin_amdgcn_exp2f(p[r]);
;     float ps = 0;
; #pragma unroll
;     for (int r = 0; r < 16; ++r) ps += p[r];
;     l_reg += ps;
;     ...
;     PK4(p, 0, paLo); PK4(p, 8, paHi);
;     ...
; }
; __device__ __forceinline__ void qkt(f32x16& p0, f32x16& p1, const char* Ks, const bf16x8* qr, int r32, int hi) {
;     p0 = f32x16{}; p1 = f32x16{};
; #pragma unroll
;     for (int d0 = 0; d0 < 4; ++d0) { const int cb = (d0 * 16 + hi * 8) * 2;
;         const bf16x8 b0 = *reinterpret_cast<const bf16x8*>(Ks + KSWZ64(r32, cb));
;         const bf16x8 b1 = *reinterpret_cast<const bf16x8*>(Ks + KSWZ64(32 + r32, cb));
;         p0 = __builtin_amdgcn_mfma_f32_32x32x16_bf16(b0, qr[d0], p0, 0, 0, 0);
;         p1 = __builtin_amdgcn_mfma_f32_32x32x16_bf16(b1, qr[d0], p1, 0, 0, 0); }
; }
; __device__ __forceinline__ int v_st(int k, int c) { const int kk = (k & ~0xC) | ((k & 4) << 1) | ((k & 8) >> 1); return ((kk >> 3) * 4 + (c >> 5)) * 512 + ((kk & 7) * 32 + (c & 31)) * 2; }
; __device__ __forceinline__ int v_rd_base(int lane) { return ((lane & 3) << 3) | (((lane >> 2) & 3) << 6) | (((lane >> 4) & 1) << 5) | (((lane >> 5) & 1) << 8); }
; template <int OFF> __device__ __forceinline__ s16x4 tr_read(int vb) {
;     s16x4 r; asm volatile("ds_read_b64_tr_b16 %0, %1 offset:%2" : "=&v"(r) : "v"(vb), "i"(OFF) : "memory"); return r;
; }
; template <int D0> __device__ __forceinline__ void pv_one(f32x16& od, int vb, bf16x8 pa0, bf16x8 pa1, bf16x8 pa2, bf16x8 pa3) {
;     const s16x4 l0 = tr_read<v_rd_off(D0, 0, 0)>(vb), h0 = tr_read<v_rd_off(D0, 0, 1)>(vb), l1 = tr_read<v_rd_off(D0, 1, 0)>(vb), h1 = tr_read<v_rd_off(D0, 1, 1)>(vb);
;     const s16x4 l2 = tr_read<v_rd_off(D0, 2, 0)>(vb), h2 = tr_read<v_rd_off(D0, 2, 1)>(vb), l3 = tr_read<v_rd_off(D0, 3, 0)>(vb), h3 = tr_read<v_rd_off(D0, 3, 1)>(vb);
; __device__ __forceinline__ void attn_unit(const bf16* __restrict__ Qb, const bf16* __restrict__ Kh, const bf16* __restrict__ Vh, bf16* __restrict__ Ob, int seq, char* lds) {
;     ...
;     SBAR(); qkt(pB0, pB1, K_lds + SHM_K, qr, r32, hi); pv_ks<0>(o, vb0, pa0); SBAR();
;     softHalf(pA1, l_reg, pa2, pa3); SBAR();
;     pv_ks<1>(o, vb0, pa1); pv_ks<2>(o, vb0, pa2); pv_ks<3>(o, vb0, pa3); SBAR();
;     softHalf(pB0, l_reg, pa0, pa1); SBAR();
	v_mfma_f32_32x32x16_bf16 v[82:97], v[122:125], v[114:117], v[82:97]
	v_mfma_f32_32x32x16_bf16 v[2:17], v[134:137], v[126:129], v[2:17]
	v_mfma_f32_32x32x16_bf16 v[18:33], v[134:137], v[118:121], v[18:33]
	v_mfma_f32_32x32x16_bf16 v[34:49], v[134:137], v[146:149], v[34:49]
	v_mfma_f32_32x32x16_bf16 v[50:65], v[134:137], v[158:161], v[50:65]
	v_exp_f32_e32 v66, v66
	v_exp_f32_e32 v67, v67
	v_exp_f32_e32 v68, v68
	v_exp_f32_e32 v69, v69
	v_exp_f32_e32 v70, v70
	v_add_f32_e32 v114, 0, v66
	v_exp_f32_e32 v71, v71
	v_add_f32_e32 v114, v67, v114
	v_exp_f32_e32 v72, v72
	v_add_f32_e32 v114, v68, v114
	v_exp_f32_e32 v73, v73
	v_add_f32_e32 v114, v69, v114
	v_exp_f32_e32 v74, v74
	v_add_f32_e32 v114, v70, v114
	v_exp_f32_e32 v75, v75
	v_add_f32_e32 v114, v71, v114
	v_exp_f32_e32 v76, v76
	v_add_f32_e32 v114, v72, v114
	v_exp_f32_e32 v77, v77
	v_add_f32_e32 v114, v73, v114
	v_exp_f32_e32 v78, v78
	v_add_f32_e32 v114, v74, v114
	v_exp_f32_e32 v79, v79
	v_add_f32_e32 v114, v75, v114
	v_exp_f32_e32 v80, v80
	v_add_f32_e32 v114, v76, v114
	v_exp_f32_e32 v81, v81
	v_add_f32_e32 v114, v77, v114
	v_add_f32_e32 v114, v78, v114
	v_add_f32_e32 v114, v79, v114
	v_add_f32_e32 v114, v80, v114
	v_cvt_pk_bf16_f32 v66, v66, v67
	v_cvt_pk_bf16_f32 v67, v68, v69
	v_cvt_pk_bf16_f32 v68, v70, v71
	v_cvt_pk_bf16_f32 v69, v72, v73
	v_add_f32_e32 v114, v81, v114
	v_permlane32_swap_b32_e32 v66, v68
	v_permlane32_swap_b32_e32 v67, v69
	v_cvt_pk_bf16_f32 v70, v74, v75
	v_cvt_pk_bf16_f32 v71, v76, v77
	v_cvt_pk_bf16_f32 v72, v78, v79
	v_cvt_pk_bf16_f32 v73, v80, v81
	v_add_f32_e32 v126, v139, v114
	v_permlane32_swap_b32_e32 v70, v72
	v_permlane32_swap_b32_e32 v71, v73
	ds_read_b64_tr_b16 v[74:75], v156 offset:0x1000
	ds_read_b64_tr_b16 v[76:77], v156 offset:0x1800
	ds_read_b64_tr_b16 v[78:79], v156 offset:0x1200
	ds_read_b64_tr_b16 v[80:81], v156 offset:0x1a00
	ds_read_b64_tr_b16 v[114:115], v156 offset:0x1400
	ds_read_b64_tr_b16 v[116:117], v156 offset:0x1c00
	ds_read_b64_tr_b16 v[118:119], v156 offset:0x1600
	ds_read_b64_tr_b16 v[120:121], v156 offset:0x1e00
	s_waitcnt lgkmcnt(0)
	s_nop 0
	v_mfma_f32_32x32x16_bf16 v[2:17], v[130:133], v[74:77], v[2:17]
	ds_read_b64_tr_b16 v[74:75], v156 offset:0x2000
	ds_read_b64_tr_b16 v[76:77], v156 offset:0x2800
	v_mfma_f32_32x32x16_bf16 v[18:33], v[130:133], v[78:81], v[18:33]
	ds_read_b64_tr_b16 v[78:79], v156 offset:0x2200
	ds_read_b64_tr_b16 v[80:81], v156 offset:0x2a00
	v_mfma_f32_32x32x16_bf16 v[34:49], v[130:133], v[114:117], v[34:49]
	ds_read_b64_tr_b16 v[114:115], v156 offset:0x2400
	ds_read_b64_tr_b16 v[116:117], v156 offset:0x2c00
	ds_read_b64_tr_b16 v[122:123], v156 offset:0x2600
	ds_read_b64_tr_b16 v[124:125], v156 offset:0x2e00
	s_waitcnt lgkmcnt(0)
	v_mfma_f32_32x32x16_bf16 v[50:65], v[130:133], v[118:121], v[50:65]
	v_mfma_f32_32x32x16_bf16 v[2:17], v[66:69], v[74:77], v[2:17]
	ds_read_b64_tr_b16 v[74:75], v156 offset:0x3000
	ds_read_b64_tr_b16 v[76:77], v156 offset:0x3800
	v_mfma_f32_32x32x16_bf16 v[18:33], v[66:69], v[78:81], v[18:33]
	ds_read_b64_tr_b16 v[78:79], v156 offset:0x3200
	ds_read_b64_tr_b16 v[80:81], v156 offset:0x3a00
	v_mfma_f32_32x32x16_bf16 v[34:49], v[66:69], v[114:117], v[34:49]
	ds_read_b64_tr_b16 v[114:115], v156 offset:0x3400
	ds_read_b64_tr_b16 v[116:117], v156 offset:0x3c00
	ds_read_b64_tr_b16 v[118:119], v156 offset:0x3600
	ds_read_b64_tr_b16 v[120:121], v156 offset:0x3e00
	s_waitcnt lgkmcnt(0)
	v_mfma_f32_32x32x16_bf16 v[50:65], v[66:69], v[122:125], v[50:65]
	v_mfma_f32_32x32x16_bf16 v[2:17], v[70:73], v[74:77], v[2:17]
	v_mfma_f32_32x32x16_bf16 v[18:33], v[70:73], v[78:81], v[18:33]
	v_mfma_f32_32x32x16_bf16 v[34:49], v[70:73], v[114:117], v[34:49]
	v_mfma_f32_32x32x16_bf16 v[50:65], v[70:73], v[118:121], v[50:65]
	v_exp_f32_e32 v66, v98
	v_exp_f32_e32 v67, v99
	v_exp_f32_e32 v68, v100
	v_exp_f32_e32 v69, v101
	v_exp_f32_e32 v70, v102
	v_add_f32_e32 v98, 0, v66
	v_exp_f32_e32 v71, v103
	v_add_f32_e32 v98, v67, v98
	v_exp_f32_e32 v72, v104
	v_add_f32_e32 v98, v68, v98
	v_exp_f32_e32 v73, v105
	v_add_f32_e32 v98, v69, v98
	v_exp_f32_e32 v74, v106
	v_add_f32_e32 v98, v70, v98
	v_exp_f32_e32 v75, v107
	v_add_f32_e32 v98, v71, v98
	v_exp_f32_e32 v76, v108
	v_add_f32_e32 v98, v72, v98
	v_exp_f32_e32 v77, v109
	v_add_f32_e32 v98, v73, v98
	v_exp_f32_e32 v78, v110
	v_add_f32_e32 v98, v74, v98
	v_exp_f32_e32 v79, v111
	v_add_f32_e32 v98, v75, v98
	v_exp_f32_e32 v80, v112
	v_add_f32_e32 v98, v76, v98
	v_exp_f32_e32 v81, v113
	v_add_f32_e32 v98, v77, v98
	v_add_f32_e32 v98, v78, v98
	v_add_f32_e32 v98, v79, v98
	v_add_f32_e32 v98, v80, v98
	v_cvt_pk_bf16_f32 v66, v66, v67
	v_cvt_pk_bf16_f32 v67, v68, v69
	v_cvt_pk_bf16_f32 v68, v70, v71
	v_cvt_pk_bf16_f32 v69, v72, v73
	v_add_f32_e32 v98, v81, v98
	v_permlane32_swap_b32_e32 v66, v68
	v_permlane32_swap_b32_e32 v67, v69
	v_cvt_pk_bf16_f32 v70, v74, v75
	v_cvt_pk_bf16_f32 v71, v76, v77
	v_cvt_pk_bf16_f32 v72, v78, v79
	v_cvt_pk_bf16_f32 v73, v80, v81
	v_add_f32_e32 v106, v126, v98
	v_permlane32_swap_b32_e32 v70, v72
	v_permlane32_swap_b32_e32 v71, v73
	ds_read_b64_tr_b16 v[74:75], v141 offset:0
	ds_read_b64_tr_b16 v[76:77], v141 offset:0x800
	ds_read_b64_tr_b16 v[78:79], v141 offset:0x200
	ds_read_b64_tr_b16 v[80:81], v141 offset:0xa00
	ds_read_b64_tr_b16 v[98:99], v141 offset:0x400
	ds_read_b64_tr_b16 v[100:101], v141 offset:0xc00
	ds_read_b64_tr_b16 v[102:103], v141 offset:0x600
	ds_read_b64_tr_b16 v[104:105], v141 offset:0xe00
	s_waitcnt lgkmcnt(0)
; #define SBAR() __builtin_amdgcn_sched_barrier(0)
; #define SBAR() __builtin_amdgcn_sched_barrier(0)
; __device__ __forceinline__ void attn_unit(const bf16* __restrict__ Qb, const bf16* __restrict__ Kh, const bf16* __restrict__ Vh, bf16* __restrict__ Ob, int seq, char* lds) {
;     ...
;     pv_ks<0>(o, vb0 + SHM_V, pa0); SBAR();
;     softHalf(pB1, l_reg, pa2, pa3); SBAR();
;     pv_ks<1>(o, vb0 + SHM_V, pa1); pv_ks<2>(o, vb0 + SHM_V, pa2); pv_ks<3>(o, vb0 + SHM_V, pa3);
;     { auto rr = __builtin_amdgcn_permlane32_swap(__float_as_uint(l_reg), __float_as_uint(l_reg), false, false); l_reg = __uint_as_float(rr[0]) + __uint_as_float(rr[1]); }
;     if (hi == 0) wsf[r32] = l_reg; asm volatile("s_waitcnt lgkmcnt(0)" ::: "memory");
	s_nop 0
	v_mfma_f32_32x32x16_bf16 v[2:17], v[66:69], v[74:77], v[2:17]
	v_mfma_f32_32x32x16_bf16 v[18:33], v[66:69], v[78:81], v[18:33]
	v_mfma_f32_32x32x16_bf16 v[34:49], v[66:69], v[98:101], v[34:49]
	v_mfma_f32_32x32x16_bf16 v[50:65], v[66:69], v[102:105], v[50:65]
	v_exp_f32_e32 v67, v82
	v_exp_f32_e32 v68, v83
	v_exp_f32_e32 v69, v84
	v_exp_f32_e32 v75, v85
	v_exp_f32_e32 v76, v86
	v_add_f32_e32 v66, 0, v67
	v_exp_f32_e32 v77, v87
	v_add_f32_e32 v66, v68, v66
	v_exp_f32_e32 v78, v88
	v_add_f32_e32 v66, v69, v66
	v_exp_f32_e32 v79, v89
	v_add_f32_e32 v66, v75, v66
	v_exp_f32_e32 v80, v90
	v_add_f32_e32 v66, v76, v66
	v_exp_f32_e32 v81, v91
	v_add_f32_e32 v66, v77, v66
	v_exp_f32_e32 v82, v92
	v_add_f32_e32 v66, v78, v66
	v_exp_f32_e32 v83, v93
	v_add_f32_e32 v66, v79, v66
	v_exp_f32_e32 v84, v94
	v_add_f32_e32 v66, v80, v66
	v_exp_f32_e32 v85, v95
	v_add_f32_e32 v66, v81, v66
	v_exp_f32_e32 v86, v96
	v_add_f32_e32 v66, v82, v66
	v_exp_f32_e32 v87, v97
	v_add_f32_e32 v66, v83, v66
	v_add_f32_e32 v66, v84, v66
	v_add_f32_e32 v66, v85, v66
	v_add_f32_e32 v66, v86, v66
	v_add_f32_e32 v66, v87, v66
	v_add_f32_e32 v66, v66, v106
	v_cvt_pk_bf16_f32 v74, v67, v68
	v_cvt_pk_bf16_f32 v75, v69, v75
	v_cvt_pk_bf16_f32 v76, v76, v77
	v_cvt_pk_bf16_f32 v77, v78, v79
	v_cvt_pk_bf16_f32 v78, v80, v81
	v_cvt_pk_bf16_f32 v79, v82, v83
	v_cvt_pk_bf16_f32 v80, v84, v85
	v_cvt_pk_bf16_f32 v81, v86, v87
	s_nop 0
	v_permlane32_swap_b32_e32 v74, v76
	v_permlane32_swap_b32_e32 v75, v77
	v_permlane32_swap_b32_e32 v78, v80
	v_permlane32_swap_b32_e32 v79, v81
	ds_read_b64_tr_b16 v[82:83], v141 offset:0x1000
	ds_read_b64_tr_b16 v[84:85], v141 offset:0x1800
	ds_read_b64_tr_b16 v[86:87], v141 offset:0x1200
	ds_read_b64_tr_b16 v[88:89], v141 offset:0x1a00
	ds_read_b64_tr_b16 v[90:91], v141 offset:0x1400
	ds_read_b64_tr_b16 v[92:93], v141 offset:0x1c00
	ds_read_b64_tr_b16 v[94:95], v141 offset:0x1600
	ds_read_b64_tr_b16 v[96:97], v141 offset:0x1e00
	s_waitcnt lgkmcnt(0)
	s_nop 0
	v_mfma_f32_32x32x16_bf16 v[2:17], v[70:73], v[82:85], v[2:17]
	ds_read_b64_tr_b16 v[82:83], v141 offset:0x2000
	ds_read_b64_tr_b16 v[84:85], v141 offset:0x2800
	v_mfma_f32_32x32x16_bf16 v[18:33], v[70:73], v[86:89], v[18:33]
	ds_read_b64_tr_b16 v[86:87], v141 offset:0x2200
	ds_read_b64_tr_b16 v[88:89], v141 offset:0x2a00
	v_mfma_f32_32x32x16_bf16 v[34:49], v[70:73], v[90:93], v[34:49]
	ds_read_b64_tr_b16 v[90:91], v141 offset:0x2400
	ds_read_b64_tr_b16 v[92:93], v141 offset:0x2c00
	ds_read_b64_tr_b16 v[98:99], v141 offset:0x2600
	ds_read_b64_tr_b16 v[100:101], v141 offset:0x2e00
	s_waitcnt lgkmcnt(0)
	v_mfma_f32_32x32x16_bf16 v[50:65], v[70:73], v[94:97], v[50:65]
	ds_read_b64_tr_b16 v[68:69], v141 offset:0x3000
	ds_read_b64_tr_b16 v[70:71], v141 offset:0x3800
	v_mfma_f32_32x32x16_bf16 v[2:17], v[74:77], v[82:85], v[2:17]
	ds_read_b64_tr_b16 v[82:83], v141 offset:0x3200
	ds_read_b64_tr_b16 v[84:85], v141 offset:0x3a00
	v_mfma_f32_32x32x16_bf16 v[18:33], v[74:77], v[86:89], v[18:33]
	ds_read_b64_tr_b16 v[86:87], v141 offset:0x3400
	ds_read_b64_tr_b16 v[88:89], v141 offset:0x3c00
	v_mfma_f32_32x32x16_bf16 v[34:49], v[74:77], v[90:93], v[34:49]
	ds_read_b64_tr_b16 v[90:91], v141 offset:0x3600
	ds_read_b64_tr_b16 v[92:93], v141 offset:0x3e00
	s_waitcnt lgkmcnt(0)
	v_mfma_f32_32x32x16_bf16 v[50:65], v[74:77], v[98:101], v[50:65]
	v_mfma_f32_32x32x16_bf16 v[2:17], v[78:81], v[68:71], v[2:17]
	v_mov_b32_e32 v67, v66
	s_nop 1
	v_permlane32_swap_b32_e32 v66, v67
	v_cmp_gt_u32_e32 vcc, 32, v145
	v_mfma_f32_32x32x16_bf16 v[18:33], v[78:81], v[82:85], v[18:33]
	v_mfma_f32_32x32x16_bf16 v[34:49], v[78:81], v[86:89], v[34:49]
	v_mfma_f32_32x32x16_bf16 v[50:65], v[78:81], v[90:93], v[50:65]
	s_and_saveexec_b64 s[10:11], vcc
	s_cbranch_execz .LBB0_529
	v_add_f32_e32 v66, v66, v67
	v_lshl_add_u32 v67, v153, 2, v143
	ds_write_b32 v67, v66 offset:49152
	s_branch .LBB0_529
